# delta consumer waves at priority 3 (instead of 1) on the balanced version
# baseline (speedup 1.0000x reference)
; #define LAS __attribute__((address_space(3)))
; __device__ __forceinline__ void delta_unit(const Params& P, LAS unsigned char* lds, int li, bool sample, int b, int h, int half, const int tid) {
;     ...
;         } else if (j >= 1 && j <= NC) {
;             LAS float* qs = (LAS float*)(lds + ((j - 1) & 1) * SET); LAS float* ks = qs + 2048; LAS float* vs = qs + 4096; LAS float* os = qs + 6144; LAS float* sc = qs + 8192;
;             const int ntok = min(MX_CH, L - (j - 1) * MX_CH);
;             f32x4 kA0, kA1, qA0, qA1, kB0, kB1, qB0, qB1; float vA, vB; f32x2 gA, gB;
;             kA0 = *(const LAS f32x4*)(ks + 8 * dq); kA1 = *(const LAS f32x4*)(ks + 8 * dq + 4); qA0 = *(const LAS f32x4*)(qs + 8 * dq); qA1 = *(const LAS f32x4*)(qs + 8 * dq + 4);
;             vA = vs[e]; gA = *(const LAS f32x2*)(sc);
.LBB0_648:
	s_setprio 3
	s_add_i32 s0, s14, -1
	s_cmpk_gt_u32 s0, 0x7f
	v_mov_b32_e32 v63, v83
	v_mov_b32_e32 v62, v84
	v_mov_b32_e32 v65, v86
	v_mov_b32_e32 v64, v87
	v_mov_b32_e32 v67, v88
	v_mov_b32_e32 v66, v89
	v_mov_b32_e32 v69, v91
	v_mov_b32_e32 v68, v81
	s_cbranch_scc1 .LBB0_651
	s_bitcmp1_b32 s0, 0
	s_cselect_b32 s1, 0x8100, 0
	s_add_i32 s0, s1, 0
	s_waitcnt lgkmcnt(4)
	v_mov_b32_e32 v24, s0
	v_lshl_add_u32 v96, v78, 2, s0
	v_lshl_add_u32 v97, v76, 2, s0
	s_waitcnt lgkmcnt(1)
	ds_read_b64 v[70:71], v24 offset:32768
	ds_read_b32 v100, v97 offset:16384
	ds_read_b128 v[24:27], v96
	ds_read_b128 v[28:31], v96 offset:16
	ds_read_b128 v[32:35], v96 offset:8208
	ds_read_b128 v[36:39], v96 offset:8192
	v_add_u32_e32 v98, s1, v90
	v_add_u32_e32 v99, s1, v92
	s_add_i32 s1, s0, 0x8008
	s_mov_b32 s25, -2
	v_mov_b32_e32 v68, v81
	v_mov_b32_e32 v69, v91
	v_mov_b32_e32 v66, v89
	v_mov_b32_e32 v67, v88
	v_mov_b32_e32 v64, v87
	v_mov_b32_e32 v65, v86
	v_mov_b32_e32 v62, v84
	v_mov_b32_e32 v63, v83
